# v19 plus 16 bytes of unreachable padding so the five GEMM K-loops sit at the baseline's offset within a 64-byte line (code placement)
# baseline (speedup 1.0000x reference)
; DI void mod0_row(const float* src, bf16_t* dst, int c0, const float4 sc0, const float4 sc1, const float4 sc2, const float4 sc3,
;                  const float4 sh0, const float4 sh1, const float4 sh2, const float4 sh3) {
;   const f32x4 v0 = __builtin_nontemporal_load((const f32x4*)(src + c0)), v1 = __builtin_nontemporal_load((const f32x4*)(src + c0 + 256));
;   const f32x4 v2 = __builtin_nontemporal_load((const f32x4*)(src + c0 + 512)), v3 = __builtin_nontemporal_load((const f32x4*)(src + c0 + 768));
;   uint2 o;
;   o.x = pk2(v0[0] * (1.f + sc0.x) + sh0.x, v0[1] * (1.f + sc0.y) + sh0.y); o.y = pk2(v0[2] * (1.f + sc0.z) + sh0.z, v0[3] * (1.f + sc0.w) + sh0.w);
;   *(uint2*)(dst + c0) = o;
;   o.x = pk2(v1[0] * (1.f + sc1.x) + sh1.x, v1[1] * (1.f + sc1.y) + sh1.y); o.y = pk2(v1[2] * (1.f + sc1.z) + sh1.z, v1[3] * (1.f + sc1.w) + sh1.w);
;   *(uint2*)(dst + c0 + 256) = o;
;   o.x = pk2(v2[0] * (1.f + sc2.x) + sh2.x, v2[1] * (1.f + sc2.y) + sh2.y); o.y = pk2(v2[2] * (1.f + sc2.z) + sh2.z, v2[3] * (1.f + sc2.w) + sh2.w);
;   *(uint2*)(dst + c0 + 512) = o;
; DI void phase_mod0(const Params& p) {
;   const int tid = opaque_tid(), lane = tid & 63, wave = __builtin_amdgcn_readfirstlane(tid >> 6);
;   const int c0 = lane * 4;
;   const int nw = gridDim.x * 8, gw = blockIdx.x * 8 + wave;
;   const int r_lo = (int)(((long)gw * TT) / nw), r_hi = (int)(((long)(gw + 1) * TT) / nw);
;   int bcur = -1;
;   float4 sc0, sc1, sc2, sc3, sh0, sh1, sh2, sh3;
;   sc0 = sc1 = sc2 = sc3 = sh0 = sh1 = sh2 = sh3 = make_float4(0.f, 0.f, 0.f, 0.f);
; #pragma unroll 1
;   for (int row = r_lo; row < r_hi; ++row) {
;     const bool isctx = row >= TL;
;     const int b = isctx ? 32 : (row >> 11);
;     if (b != bcur) {
;       bcur = b;
;       const float* md = p.mod + (size_t)b * 3072;
;       sh0 = *(const float4*)(md + c0); sh1 = *(const float4*)(md + c0 + 256); sh2 = *(const float4*)(md + c0 + 512); sh3 = *(const float4*)(md + c0 + 768);
;       sc0 = *(const float4*)(md + 1024 + c0); sc1 = *(const float4*)(md + 1024 + c0 + 256); sc2 = *(const float4*)(md + 1024 + c0 + 512); sc3 = *(const float4*)(md + 1024 + c0 + 768);
;     }
;     const float* srcp = isctx ? (p.ctx + (size_t)(row - TL) * 1024) : (p.x + (size_t)row * 1024);
;     mod0_row(srcp, p.u + (size_t)row * 1024, c0, sc0, sc1, sc2, sc3, sh0, sh1, sh2, sh3);
;   }
.Lmod0_f2:
	s_lshl_b64 s[14:15], s[14:15], 11
	global_load_dwordx4 v[56:59], v0, s[12:13] nt
	global_load_dwordx4 v[60:63], v0, s[12:13] offset:1024 nt
	global_load_dwordx4 v[64:67], v0, s[12:13] offset:2048 nt
	global_load_dwordx4 v[68:71], v0, s[12:13] offset:3072 nt
	s_add_u32 s12, s12, 0x1000
	s_addc_u32 s13, s13, 0
	global_load_dwordx4 v[72:75], v0, s[12:13] nt
	global_load_dwordx4 v[76:79], v0, s[12:13] offset:1024 nt
	global_load_dwordx4 v[80:83], v0, s[12:13] offset:2048 nt
	global_load_dwordx4 v[84:87], v0, s[12:13] offset:3072 nt
	s_add_u32 s12, s12, 0x1000
	s_addc_u32 s13, s13, 0
	global_load_dwordx4 v[88:91], v0, s[12:13] nt
	global_load_dwordx4 v[92:95], v0, s[12:13] offset:1024 nt
	global_load_dwordx4 v[96:99], v0, s[12:13] offset:2048 nt
	global_load_dwordx4 v[100:103], v0, s[12:13] offset:3072 nt
	s_add_u32 s12, s12, 0x1000
	s_addc_u32 s13, s13, 0
	global_load_dwordx4 v[148:151], v0, s[12:13] nt
	global_load_dwordx4 v[152:155], v0, s[12:13] offset:1024 nt
	global_load_dwordx4 v[156:159], v0, s[12:13] offset:2048 nt
	global_load_dwordx4 v[160:163], v0, s[12:13] offset:3072 nt
	s_movk_i32 s100, 0x800
	s_mov_b32 s101, 0
	v_lshl_add_u64 v[104:105], v[34:35], 0, s[14:15]
	s_waitcnt vmcnt(16)
	v_pk_add_f32 v[108:109], v[22:23], 1.0 op_sel_hi:[1,0]
	v_pk_add_f32 v[110:111], v[24:25], 1.0 op_sel_hi:[1,0]
	v_pk_add_f32 v[112:113], v[10:11], 1.0 op_sel_hi:[1,0]
	v_pk_add_f32 v[114:115], v[12:13], 1.0 op_sel_hi:[1,0]
	v_pk_add_f32 v[116:117], v[18:19], 1.0 op_sel_hi:[1,0]
	v_pk_add_f32 v[118:119], v[20:21], 1.0 op_sel_hi:[1,0]
	v_pk_add_f32 v[120:121], v[30:31], 1.0 op_sel_hi:[1,0]
	v_pk_add_f32 v[122:123], v[32:33], 1.0 op_sel_hi:[1,0]
	s_waitcnt vmcnt(15)
	v_pk_fma_f32 v[124:125], v[108:109], v[56:57], v[2:3]
	v_pk_fma_f32 v[126:127], v[110:111], v[58:59], v[4:5]
	v_cvt_pk_bf16_f32 v128, v124, v125
	v_cvt_pk_bf16_f32 v129, v126, v127
	global_store_dwordx2 v[104:105], v[128:129], off
	s_waitcnt vmcnt(15)
	v_pk_fma_f32 v[124:125], v[112:113], v[60:61], v[6:7]
	v_pk_fma_f32 v[126:127], v[114:115], v[62:63], v[8:9]
	v_cvt_pk_bf16_f32 v130, v124, v125
	v_cvt_pk_bf16_f32 v131, v126, v127
	global_store_dwordx2 v[104:105], v[130:131], off offset:512
	s_waitcnt vmcnt(15)
	v_pk_fma_f32 v[124:125], v[116:117], v[64:65], v[14:15]
	v_pk_fma_f32 v[126:127], v[118:119], v[66:67], v[16:17]
	v_cvt_pk_bf16_f32 v128, v124, v125
	v_cvt_pk_bf16_f32 v129, v126, v127
	global_store_dwordx2 v[104:105], v[128:129], off offset:1024
	s_waitcnt vmcnt(15)
	v_pk_fma_f32 v[124:125], v[120:121], v[68:69], v[26:27]
	v_pk_fma_f32 v[126:127], v[122:123], v[70:71], v[28:29]
	v_cvt_pk_bf16_f32 v130, v124, v125
	v_cvt_pk_bf16_f32 v131, v126, v127
	global_store_dwordx2 v[104:105], v[130:131], off offset:1536
	v_lshl_add_u64 v[104:105], v[104:105], 0, s[100:101]
	s_waitcnt vmcnt(15)
	v_pk_fma_f32 v[124:125], v[108:109], v[72:73], v[2:3]
	v_pk_fma_f32 v[126:127], v[110:111], v[74:75], v[4:5]
	v_cvt_pk_bf16_f32 v128, v124, v125
	v_cvt_pk_bf16_f32 v129, v126, v127
	global_store_dwordx2 v[104:105], v[128:129], off
	s_waitcnt vmcnt(15)
	v_pk_fma_f32 v[124:125], v[112:113], v[76:77], v[6:7]
	v_pk_fma_f32 v[126:127], v[114:115], v[78:79], v[8:9]
	v_cvt_pk_bf16_f32 v130, v124, v125
	v_cvt_pk_bf16_f32 v131, v126, v127
	global_store_dwordx2 v[104:105], v[130:131], off offset:512
	s_waitcnt vmcnt(15)
	v_pk_fma_f32 v[124:125], v[116:117], v[80:81], v[14:15]
	v_pk_fma_f32 v[126:127], v[118:119], v[82:83], v[16:17]
	v_cvt_pk_bf16_f32 v128, v124, v125
	v_cvt_pk_bf16_f32 v129, v126, v127
	global_store_dwordx2 v[104:105], v[128:129], off offset:1024
	s_waitcnt vmcnt(15)
	v_pk_fma_f32 v[124:125], v[120:121], v[84:85], v[26:27]
	v_pk_fma_f32 v[126:127], v[122:123], v[86:87], v[28:29]
	v_cvt_pk_bf16_f32 v130, v124, v125
	v_cvt_pk_bf16_f32 v131, v126, v127
	global_store_dwordx2 v[104:105], v[130:131], off offset:1536
	v_lshl_add_u64 v[104:105], v[104:105], 0, s[100:101]
	s_waitcnt vmcnt(15)
	v_pk_fma_f32 v[124:125], v[108:109], v[88:89], v[2:3]
	v_pk_fma_f32 v[126:127], v[110:111], v[90:91], v[4:5]
	v_cvt_pk_bf16_f32 v128, v124, v125
	v_cvt_pk_bf16_f32 v129, v126, v127
	global_store_dwordx2 v[104:105], v[128:129], off
	s_waitcnt vmcnt(15)
	v_pk_fma_f32 v[124:125], v[112:113], v[92:93], v[6:7]
	v_pk_fma_f32 v[126:127], v[114:115], v[94:95], v[8:9]
	v_cvt_pk_bf16_f32 v130, v124, v125
	v_cvt_pk_bf16_f32 v131, v126, v127
	global_store_dwordx2 v[104:105], v[130:131], off offset:512
	s_waitcnt vmcnt(15)
	v_pk_fma_f32 v[124:125], v[116:117], v[96:97], v[14:15]
	v_pk_fma_f32 v[126:127], v[118:119], v[98:99], v[16:17]
	v_cvt_pk_bf16_f32 v128, v124, v125
	v_cvt_pk_bf16_f32 v129, v126, v127
	global_store_dwordx2 v[104:105], v[128:129], off offset:1024
	s_waitcnt vmcnt(15)
	v_pk_fma_f32 v[124:125], v[120:121], v[100:101], v[26:27]
	v_pk_fma_f32 v[126:127], v[122:123], v[102:103], v[28:29]
	v_cvt_pk_bf16_f32 v130, v124, v125
	v_cvt_pk_bf16_f32 v131, v126, v127
	global_store_dwordx2 v[104:105], v[130:131], off offset:1536
	v_lshl_add_u64 v[104:105], v[104:105], 0, s[100:101]
	s_waitcnt vmcnt(15)
	v_pk_fma_f32 v[124:125], v[108:109], v[148:149], v[2:3]
	v_pk_fma_f32 v[126:127], v[110:111], v[150:151], v[4:5]
	v_cvt_pk_bf16_f32 v128, v124, v125
	v_cvt_pk_bf16_f32 v129, v126, v127
	global_store_dwordx2 v[104:105], v[128:129], off
	s_waitcnt vmcnt(15)
	v_pk_fma_f32 v[124:125], v[112:113], v[152:153], v[6:7]
	v_pk_fma_f32 v[126:127], v[114:115], v[154:155], v[8:9]
	v_cvt_pk_bf16_f32 v130, v124, v125
	v_cvt_pk_bf16_f32 v131, v126, v127
	global_store_dwordx2 v[104:105], v[130:131], off offset:512
	s_waitcnt vmcnt(15)
	v_pk_fma_f32 v[124:125], v[116:117], v[156:157], v[14:15]
	v_pk_fma_f32 v[126:127], v[118:119], v[158:159], v[16:17]
	v_cvt_pk_bf16_f32 v128, v124, v125
	v_cvt_pk_bf16_f32 v129, v126, v127
	global_store_dwordx2 v[104:105], v[128:129], off offset:1024
	s_waitcnt vmcnt(15)
	v_pk_fma_f32 v[124:125], v[120:121], v[160:161], v[26:27]
	v_pk_fma_f32 v[126:127], v[122:123], v[162:163], v[28:29]
	v_cvt_pk_bf16_f32 v130, v124, v125
	v_cvt_pk_bf16_f32 v131, v126, v127
	global_store_dwordx2 v[104:105], v[130:131], off offset:1536
	s_add_u32 s6, s6, 4
	s_addc_u32 s7, s7, 0
	s_add_u32 s10, s10, 0x4000
	s_addc_u32 s11, s11, 0
	s_cmp_ge_i32 s6, s8
	s_cbranch_scc1 .LBB0_31
	s_branch .LBB0_24
	s_nop 0
	s_nop 0
	s_nop 0
	s_nop 0
